# grid barrier after phase 3: the 17th local arriver issues one early unwaited L2 write-back (pre-flush) so the leader's write-back after the last arrival is shorter
# speedup vs baseline: 1.0010x; 1.0010x over previous
; __device__ __forceinline__ unsigned xb_ld(unsigned* p)              { return __hip_atomic_load(p, __ATOMIC_RELAXED, __HIP_MEMORY_SCOPE_AGENT); }
; __device__ __forceinline__ unsigned xb_add(unsigned* p, unsigned v) { return __hip_atomic_fetch_add(p, v, __ATOMIC_RELAXED, __HIP_MEMORY_SCOPE_AGENT); }
; #define XB_SPIN(cond, bar) do { unsigned _sp = 0; while (cond) { __builtin_amdgcn_s_sleep(1); \
;     if ((++_sp & 255u) == 0u) { if (xb_ld(&(bar)[XB_TMO])) break; if (_sp > XB_SPIN_CAP) { atomicAdd(&(bar)[XB_TMO], 1u); break; } } } } while (0)
; __device__ __forceinline__ void xcd_barrier(const XcdBarrier& b) {
;     ...
;         const unsigned old = xb_add(&bar[XB_XSUB(b.x)], 1u);
;         const unsigned gen = old / nloc;
;         if (old + 1u == (gen + 1u) * nloc) {
;             __builtin_amdgcn_fence(__ATOMIC_RELEASE, "agent");
;             asm volatile("s_waitcnt vmcnt(0)" ::: "memory");
;             const unsigned og = xb_add(&bar[XB_TOP], 1u);
;             const unsigned tg = og / nx;
;             if (og + 1u == (tg + 1u) * nx) xb_add(&bar[XB_TOPGEN], 1u);
;             else XB_SPIN(xb_ld(&bar[XB_TOPGEN]) == tg, bar);
;             __builtin_amdgcn_fence(__ATOMIC_ACQUIRE, "agent");
;             xb_add(&bar[XB_XGEN(b.x)], 1u);
;             asm volatile("s_waitcnt vmcnt(0)" ::: "memory");
;         } else {
;             XB_SPIN(xb_ld(&bar[XB_XGEN(b.x)]) == gen, bar);
;             __builtin_amdgcn_fence(__ATOMIC_ACQUIRE, "agent");
;             asm volatile("s_waitcnt vmcnt(0)" ::: "memory");
;         }
.LBB0_376:
	s_or_b64 exec, exec, s[8:9]
	v_cvt_f32_u32_e32 v4, v2
	s_waitcnt vmcnt(0)
	v_readfirstlane_b32 s6, v3
	v_sub_u32_e32 v3, 0, v2
	v_rcp_iflag_f32_e32 v4, v4
	v_add_u32_e32 v5, s6, v1
	v_mul_f32_e32 v4, 0x4f7ffffe, v4
	v_cvt_u32_f32_e32 v4, v4
	v_mul_lo_u32 v1, v3, v4
	v_mul_hi_u32 v1, v4, v1
	v_add_u32_e32 v1, v4, v1
	v_mul_hi_u32 v1, v5, v1
	v_mul_lo_u32 v3, v1, v2
	v_sub_u32_e32 v3, v5, v3
	v_add_u32_e32 v4, 1, v1
	v_cmp_ge_u32_e32 vcc, v3, v2
	s_nop 1
	v_cndmask_b32_e32 v1, v1, v4, vcc
	v_sub_u32_e32 v4, v3, v2
	v_cndmask_b32_e32 v3, v3, v4, vcc
	v_add_u32_e32 v4, 1, v1
	v_cmp_ge_u32_e32 vcc, v3, v2
	v_add_u32_e32 v3, 1, v5
	s_nop 0
	v_cndmask_b32_e32 v1, v1, v4, vcc
	v_mul_lo_u32 v4, v2, v1
	v_add_u32_e32 v2, v4, v2
	v_cmp_ne_u32_e32 vcc, v3, v2
	s_and_saveexec_b64 s[6:7], vcc
	s_xor_b64 s[6:7], exec, s[6:7]
	s_cbranch_execz .LBB0_390
	buffer_inv sc1
	v_and_b32_e32 v3, 31, v5
	v_cmp_eq_u32_e32 vcc, 16, v3
	s_and_saveexec_b64 s[8:9], vcc
	s_cbranch_execz .Lpf_skip3
	buffer_wbl2 sc1
.Lpf_skip3:
	s_or_b64 exec, exec, s[8:9]
	s_waitcnt lgkmcnt(0)
	v_add_u32_e32 v1, 1, v1
	v_mul_lo_u32 v1, v1, v0
	s_add_u32 s12, s50, 0xfc3400
	s_addc_u32 s13, s51, 0
	v_mov_b32_e32 v0, 0
	global_load_dword v0, v0, s[12:13] sc1
	s_waitcnt vmcnt(0)
	v_cmp_lt_u32_e32 vcc, v0, v1
	s_and_saveexec_b64 s[8:9], vcc
	s_cbranch_execz .LBB0_389
	s_add_u32 s10, s50, 0xfc0200
	s_addc_u32 s11, s51, 0
	s_mov_b32 s28, 1
	s_mov_b64 s[14:15], 0
	v_mov_b32_e32 v0, 0
	s_branch .LBB0_380
